# EW2 + EW3(l<3) row loops: next-row loads software-prefetched into shadow VGPRs (two rows in flight)
# speedup vs baseline: 1.0007x; 1.0007x over previous
; __device__ __forceinline__ float bf_lo(unsigned w) { return __uint_as_float(w << 16); }
; __device__ __forceinline__ float bf_hi(unsigned w) { return __uint_as_float(w & 0xffff0000u); }
; __device__ __forceinline__ void ew_phase(const Frame& F, const bf16_t* f, const float* gpost, float alpha, const float* hin, float* hout, const float* gpre, bf16_t* xn, ...
;     ...
;     f32x4 gp[4], gq[4];
; #pragma unroll
;     for (int j = 0; j < 4; ++j) { gp[j] = ((const f32x4*)gpost)[F.lane + 64 * j]; gq[j] = gpre ? ((const f32x4*)gpre)[F.lane + 64 * j] : (f32x4){0.f, 0.f, 0.f, 0.f}; }
;     const int it_n = prow0 >= 0 ? 8 : (T + F.NGW - 1) / F.NGW;
;     for (int it_ = 0; it_ < it_n; ++it_) {
;         const int m = prow0 >= 0 ? prow0 + F.wave * 8 + it_ : F.gw + it_ * F.NGW; if (m >= T) break;
;         const u32x2* fr = (const u32x2*)(f + (size_t)m * DM) + F.lane; const f32x4* hr = (const f32x4*)(hin + (size_t)m * DM) + F.lane;
;         f32x4 fv[4], hv[4]; float s = 0.f;
; #pragma unroll
;         for (int j = 0; j < 4; ++j) { const u32x2 w = fr[64 * j]; hv[j] = in24 ? load24(h24 + (size_t)m * (DM * 3), F.lane + 64 * j) : hr[64 * j]; fv[j] = (f32x4){bf_lo(w.x), bf_hi(w.x), bf_lo(w.y), bf_hi(w.y)};
.LBB0_901:
	s_or_b64 exec, exec, s[0:1]
	v_mov_b32_e32 v0, v224
	s_barrier
	s_nop 0
	v_readfirstlane_b32 s0, v0
	s_ashr_i32 s11, s0, 6
	v_readlane_b32 s0, v251, 39
	s_add_i32 s10, s11, s0
	v_readlane_b32 s0, v252, 6
	v_and_b32_e32 v92, 63, v0
	v_readlane_b32 s1, v252, 7
	s_and_b64 vcc, exec, s[0:1]
	v_lshlrev_b32_e32 v34, 3, v92
	s_mov_b64 s[0:1], -1
	s_cbranch_vccz .LBB0_914
	v_or_b32_e32 v95, 64, v92
	v_or_b32_e32 v94, 0x80, v92
	v_or_b32_e32 v93, 0xc0, v92
	s_and_b64 vcc, exec, s[22:23]
	v_mul_hi_u32_u24_e32 v37, 12, v92
	v_mul_u32_u24_e32 v36, 12, v92
	v_mul_hi_u32_u24_e32 v39, 12, v95
	v_mul_u32_u24_e32 v38, 12, v95
	v_mul_hi_u32_u24_e32 v41, 12, v94
	v_mul_u32_u24_e32 v40, 12, v94
	v_mul_hi_u32_u24_e32 v43, 12, v93
	v_mul_u32_u24_e32 v42, 12, v93
	s_cbranch_vccnz .LBB0_908
	v_readlane_b32 s36, v251, 23
	v_readlane_b32 s44, v251, 31
	v_readlane_b32 s45, v251, 32
	s_add_u32 s0, s44, s4
	v_readlane_b32 s2, v255, 2
	s_addc_u32 s1, s45, s5
	v_readlane_b32 s3, v255, 3
	s_lshl_b32 s72, s2, 10
	s_lshl_b64 s[2:3], s[72:73], 2
	s_add_u32 s2, s60, s2
	v_lshlrev_b32_e32 v0, 4, v92
	s_addc_u32 s3, s61, s3
	global_load_dwordx4 v[2:5], v0, s[0:1]
	global_load_dwordx4 v[6:9], v0, s[0:1] offset:1024
	global_load_dwordx4 v[10:13], v0, s[2:3]
	global_load_dwordx4 v[14:17], v0, s[2:3] offset:1024
	global_load_dwordx4 v[18:21], v0, s[0:1] offset:2048
	global_load_dwordx4 v[22:25], v0, s[0:1] offset:3072
	global_load_dwordx4 v[26:29], v0, s[2:3] offset:2048
	global_load_dwordx4 v[30:33], v0, s[2:3] offset:3072
	v_mov_b32_e32 v35, v1
	s_lshl_b32 s0, s11, 3
	v_readlane_b32 s1, v254, 25
	v_lshl_add_u64 v[44:45], s[58:59], 0, v[34:35]
	v_lshl_add_u64 v[46:47], s[20:21], 0, v[34:35]
	s_add_i32 s2, s1, s0
	s_mov_b32 s3, 0
	s_mov_b32 s12, s10
	v_readlane_b32 s37, v251, 24
	v_readlane_b32 s38, v251, 25
	v_readlane_b32 s39, v251, 26
	v_readlane_b32 s40, v251, 27
	v_readlane_b32 s41, v251, 28
	v_readlane_b32 s42, v251, 29
	v_readlane_b32 s43, v251, 30
	v_readlane_b32 s46, v251, 33
	v_readlane_b32 s47, v251, 34
	v_readlane_b32 s48, v251, 35
	v_readlane_b32 s49, v251, 36
	v_readlane_b32 s50, v251, 37
	v_readlane_b32 s51, v251, 38
	v_readlane_b32 s0, v252, 11
	v_readlane_b32 s1, v252, 12
	s_and_b64 s[0:1], s[0:1], exec
	s_cselect_b32 s8, s2, s12
	s_cselect_b32 s9, 1, 0x800
	s_lshl_b32 s0, s9, 11
	s_mul_i32 s1, s9, 0xc00
	v_mov_b32_e32 v206, s9
	v_mov_b32_e32 v192, s0
	v_mov_b32_e32 v193, 0
	v_mov_b32_e32 v194, s1
	v_mov_b32_e32 v195, 0
	s_cmpk_gt_i32 s8, 0x3fff
	s_cbranch_scc1 .Lew3_pf_none
	s_ashr_i32 s9, s8, 31
	s_lshl_b64 s[0:1], s[8:9], 11
	v_lshl_add_u64 v[196:197], v[44:45], 0, s[0:1]
	s_mul_i32 s0, s8, 0xc00
	s_mul_hi_i32 s1, s8, 0xc00
	s_add_u32 s0, s13, s0
	s_addc_u32 s1, s14, s1
	v_lshl_add_u64 v[198:199], s[0:1], 0, v[36:37]
	v_lshl_add_u64 v[200:201], s[0:1], 0, v[38:39]
	v_lshl_add_u64 v[202:203], s[0:1], 0, v[40:41]
	v_lshl_add_u64 v[204:205], s[0:1], 0, v[42:43]
	global_load_dwordx2 v[168:169], v[196:197], off
	global_load_dwordx2 v[170:171], v[198:199], off
	global_load_dwordx2 v[172:173], v[198:199], off offset:4
	global_load_dwordx2 v[174:175], v[196:197], off offset:512
	global_load_dwordx2 v[176:177], v[200:201], off
	global_load_dwordx2 v[178:179], v[200:201], off offset:4
	global_load_dwordx2 v[180:181], v[196:197], off offset:1024
	global_load_dwordx2 v[182:183], v[202:203], off
	global_load_dwordx2 v[184:185], v[202:203], off offset:4
	global_load_dwordx2 v[186:187], v[196:197], off offset:1536
	global_load_dwordx2 v[188:189], v[204:205], off
	global_load_dwordx2 v[190:191], v[204:205], off offset:4
	s_waitcnt vmcnt(0)
.Lew3_pf_none:
	s_branch .LBB0_905
.LBB0_904:
	s_andn2_b64 vcc, exec, s[0:1]
	s_cbranch_vccz .LBB0_907
.LBB0_905:
	v_readlane_b32 s0, v252, 11
	s_add_i32 s6, s2, s3
	v_readlane_b32 s1, v252, 12
	s_and_b64 s[0:1], s[0:1], exec
	s_cselect_b32 s8, s6, s12
	s_cmpk_gt_i32 s8, 0x3fff
	s_mov_b64 s[0:1], -1
	s_cbranch_scc1 .LBB0_904
	s_ashr_i32 s9, s8, 31
	s_lshl_b64 s[6:7], s[8:9], 11
	s_mul_i32 s0, s8, 0xc00
	s_mul_hi_i32 s1, s8, 0xc00
	s_add_u32 s0, s13, s0
	s_addc_u32 s1, s14, s1
	v_lshl_add_u64 v[48:49], s[0:1], 0, v[36:37]
	v_lshl_add_u64 v[58:59], s[0:1], 0, v[38:39]
	s_waitcnt vmcnt(8)
	v_mov_b64_e32 v[56:57], v[168:169]
	v_mov_b64_e32 v[52:53], v[170:171]
	v_mov_b64_e32 v[54:55], v[172:173]
	v_mov_b64_e32 v[64:65], v[174:175]
	v_mov_b64_e32 v[62:63], v[176:177]
	v_mov_b64_e32 v[66:67], v[178:179]
	v_mov_b64_e32 v[72:73], v[180:181]
	v_mov_b64_e32 v[76:77], v[182:183]
	v_mov_b64_e32 v[78:79], v[184:185]
	v_mov_b64_e32 v[80:81], v[186:187]
	v_mov_b64_e32 v[166:167], v[188:189]
	v_mov_b64_e32 v[82:83], v[190:191]
	v_readfirstlane_b32 s9, v206
	s_add_i32 s9, s8, s9
	s_cmpk_gt_i32 s9, 0x3fff
	s_cbranch_scc1 .Lew3_pf_skip
	s_cmp_eq_u32 s3, 7
	s_cbranch_scc1 .Lew3_pf_skip
	v_lshl_add_u64 v[196:197], v[196:197], 0, v[192:193]
	v_lshl_add_u64 v[198:199], v[198:199], 0, v[194:195]
	v_lshl_add_u64 v[200:201], v[200:201], 0, v[194:195]
	v_lshl_add_u64 v[202:203], v[202:203], 0, v[194:195]
	v_lshl_add_u64 v[204:205], v[204:205], 0, v[194:195]
	global_load_dwordx2 v[168:169], v[196:197], off
	global_load_dwordx2 v[170:171], v[198:199], off
	global_load_dwordx2 v[172:173], v[198:199], off offset:4
	global_load_dwordx2 v[174:175], v[196:197], off offset:512
	global_load_dwordx2 v[176:177], v[200:201], off
	global_load_dwordx2 v[178:179], v[200:201], off offset:4
	global_load_dwordx2 v[180:181], v[196:197], off offset:1024
	global_load_dwordx2 v[182:183], v[202:203], off
	global_load_dwordx2 v[184:185], v[202:203], off offset:4
	global_load_dwordx2 v[186:187], v[196:197], off offset:1536
	global_load_dwordx2 v[188:189], v[204:205], off
	global_load_dwordx2 v[190:191], v[204:205], off offset:4
; __device__ __forceinline__ float bf_lo(unsigned w) { return __uint_as_float(w << 16); }
; __device__ __forceinline__ float bf_hi(unsigned w) { return __uint_as_float(w & 0xffff0000u); }
; __device__ __forceinline__ f32x4 load24(const unsigned char* rowp, int blk) { const unsigned* p = (const unsigned*)(rowp + (size_t)blk * 12); const unsigned w0 = p[0], w1 = p[1], w2 = p[2];
;     return (f32x4){__uint_as_float((w0 & 0xffffffu) << 8), __uint_as_float(((w0 >> 24) | ((w1 & 0xffffu) << 8)) << 8), __uint_as_float(((w1 >> 16) | ((w2 & 0xffu) << 16)) << 8), __uint_as_float((w2 >> 8) << 8)}; }
; __device__ __forceinline__ void ew_phase(const Frame& F, const bf16_t* f, const float* gpost, float alpha, const float* hin, float* hout, const float* gpre, bf16_t* xn, ...
;     ...
;         for (int j = 0; j < 4; ++j) { const u32x2 w = fr[64 * j]; hv[j] = in24 ? load24(h24 + (size_t)m * (DM * 3), F.lane + 64 * j) : hr[64 * j]; fv[j] = (f32x4){bf_lo(w.x), bf_hi(w.x), bf_lo(w.y), bf_hi(w.y)};
;             s += (fv[j].x * fv[j].x + fv[j].y * fv[j].y) + (fv[j].z * fv[j].z + fv[j].w * fv[j].w); }
;         const float rstd = alpha / sqrtf(wave_sum(s) * (1.f / DM) + RMS_EPS);
.Lew3_pf_skip:
	s_mov_b32 s8, 0xff00
	s_add_i32 s3, s3, 1
	s_addk_i32 s12, 0x800
	s_cmp_eq_u32 s3, 8
	v_lshrrev_b32_e32 v51, 8, v53
	v_lshlrev_b32_e32 v0, 24, v55
	v_lshlrev_b32_e32 v35, 16, v54
	v_and_b32_e32 v51, 0xffff00, v51
	v_and_b32_sdwa v53, v52, s8 dst_sel:DWORD dst_unused:UNUSED_PAD src0_sel:WORD_1 src1_sel:DWORD
	v_lshlrev_b32_e32 v50, 8, v52
	v_or_b32_e32 v52, v0, v51
	v_or_b32_e32 v51, v35, v53
	v_and_b32_e32 v53, 0xffffff00, v55
	v_lshlrev_b32_e32 v54, 16, v56
	v_and_b32_e32 v55, 0xffff0000, v56
	v_lshlrev_b32_e32 v56, 16, v57
	v_and_b32_e32 v57, 0xffff0000, v57
	v_mul_f32_e32 v0, v57, v57
	v_lshrrev_b32_e32 v61, 8, v63
	v_pk_fma_f32 v[90:91], v[56:57], v[56:57], v[0:1] op_sel_hi:[1,1,0]
	v_lshlrev_b32_e32 v0, 24, v67
	v_lshlrev_b32_e32 v35, 16, v66
	v_and_b32_e32 v61, 0xffff00, v61
	v_and_b32_sdwa v63, v62, s8 dst_sel:DWORD dst_unused:UNUSED_PAD src0_sel:WORD_1 src1_sel:DWORD
	v_lshlrev_b32_e32 v60, 8, v62
	v_or_b32_e32 v62, v0, v61
	v_or_b32_e32 v61, v35, v63
	v_and_b32_e32 v63, 0xffffff00, v67
	v_lshlrev_b32_e32 v67, 16, v65
	v_lshlrev_b32_e32 v66, 16, v64
	v_and_b32_e32 v65, 0xffff0000, v65
	v_and_b32_e32 v64, 0xffff0000, v64
	v_pk_mul_f32 v[70:71], v[64:65], v[64:65]
	v_lshlrev_b32_e32 v88, 16, v73
	v_pk_fma_f32 v[96:97], v[66:67], v[66:67], v[70:71]
	v_lshl_add_u64 v[70:71], s[0:1], 0, v[40:41]
	v_lshl_add_u64 v[68:69], s[0:1], 0, v[42:43]
	v_and_b32_e32 v89, 0xffff0000, v73
	v_lshlrev_b32_e32 v86, 16, v72
	v_and_b32_e32 v87, 0xffff0000, v72
	v_mov_b32_e32 v100, v90
	v_pk_add_f32 v[96:97], v[96:97], v[96:97] op_sel:[0,1] op_sel_hi:[1,0]
	v_lshrrev_b32_e32 v75, 8, v77
	v_lshlrev_b32_e32 v74, 8, v76
	v_lshlrev_b32_e32 v0, 24, v79
	v_lshlrev_b32_e32 v35, 16, v78
	v_and_b32_e32 v75, 0xffff00, v75
	v_and_b32_sdwa v76, v76, s8 dst_sel:DWORD dst_unused:UNUSED_PAD src0_sel:WORD_1 src1_sel:DWORD
	v_or_b32_e32 v78, v0, v75
	v_or_b32_e32 v75, v35, v76
	v_lshlrev_b32_e32 v85, 16, v80
	v_mov_b32_e32 v101, v85
	v_and_b32_e32 v79, 0xffffff00, v79
	v_lshrrev_b32_e32 v73, 8, v167
	v_lshlrev_b32_e32 v0, 24, v83
	v_and_b32_e32 v73, 0xffff00, v73
	v_lshlrev_b32_e32 v72, 8, v166
	v_and_b32_sdwa v77, v166, s8 dst_sel:DWORD dst_unused:UNUSED_PAD src0_sel:WORD_1 src1_sel:DWORD
	v_or_b32_e32 v76, v0, v73
	v_mul_f32_e32 v0, v55, v55
	v_lshlrev_b32_e32 v35, 16, v82
	v_pk_fma_f32 v[98:99], v[54:55], v[54:55], v[0:1] op_sel_hi:[1,1,0]
	v_or_b32_e32 v73, v35, v77
	v_and_b32_e32 v77, 0xffffff00, v83
	v_and_b32_e32 v83, 0xffff0000, v80
	v_mov_b32_e32 v84, v98
	v_mul_f32_e32 v35, v83, v83
	v_pk_add_f32 v[90:91], v[98:99], v[90:91]
	v_pk_mul_f32 v[98:99], v[84:85], v[100:101]
	v_mov_b32_e32 v97, v35
	v_mov_b32_e32 v91, v99
	v_mul_f32_e32 v0, v87, v87
	v_lshlrev_b32_e32 v80, 16, v81
	v_and_b32_e32 v81, 0xffff0000, v81
	v_pk_add_f32 v[90:91], v[90:91], v[96:97]
	v_pk_fma_f32 v[96:97], v[86:87], v[86:87], v[0:1] op_sel_hi:[1,1,0]
	v_mul_f32_e32 v0, v89, v89
	v_mul_f32_e32 v82, v80, v80
	v_mul_f32_e32 v102, v81, v81
	v_pk_fma_f32 v[98:99], v[88:89], v[88:89], v[0:1] op_sel_hi:[1,1,0]
	v_and_b32_e32 v0, 64, v230
	v_mov_b32_e32 v97, v82
	v_mov_b32_e32 v99, v102
	v_add_u32_e32 v82, 64, v0
	v_xor_b32_e32 v0, 1, v230
	v_pk_add_f32 v[96:97], v[96:97], v[98:99]
	v_cmp_lt_i32_e32 vcc, v0, v82
	v_pk_add_f32 v[90:91], v[90:91], v[96:97]
	s_nop 0
	v_cndmask_b32_e32 v0, v230, v0, vcc
	v_add_f32_e32 v35, v90, v91
	v_lshlrev_b32_e32 v0, 2, v0
	s_nop 1
	v_add_f32_dpp v84, v35, v35 quad_perm:[1,0,3,2] row_mask:0xf bank_mask:0xf
	v_xor_b32_e32 v35, 2, v230
	v_cmp_lt_i32_e32 vcc, v35, v82
	s_nop 1
	v_cndmask_b32_e32 v35, v230, v35, vcc
	v_lshlrev_b32_e32 v35, 2, v35
	s_nop 1
	v_add_f32_dpp v90, v84, v84 quad_perm:[2,3,0,1] row_mask:0xf bank_mask:0xf
	v_xor_b32_e32 v84, 4, v230
	v_cmp_lt_i32_e32 vcc, v84, v82
	s_nop 1
	v_cndmask_b32_e32 v84, v230, v84, vcc
	v_lshlrev_b32_e32 v84, 2, v84
	s_nop 1
	v_add_f32_dpp v91, v90, v90 row_half_mirror row_mask:0xf bank_mask:0xf
	v_xor_b32_e32 v90, 8, v230
	v_cmp_lt_i32_e32 vcc, v90, v82
	s_nop 1
	v_cndmask_b32_e32 v90, v230, v90, vcc
	v_lshlrev_b32_e32 v90, 2, v90
	s_nop 1
	v_add_f32_dpp v91, v91, v91 row_mirror row_mask:0xf bank_mask:0xf
	v_xor_b32_e32 v96, 16, v230
	v_cmp_lt_i32_e32 vcc, v96, v82
	s_nop 1
	v_cndmask_b32_e32 v96, v230, v96, vcc
	v_lshlrev_b32_e32 v97, 2, v96
	ds_bpermute_b32 v96, v97, v91
	s_waitcnt lgkmcnt(0)
	v_add_f32_e32 v91, v91, v96
	v_xor_b32_e32 v96, 32, v230
	v_cmp_lt_i32_e32 vcc, v96, v82
	s_nop 1
	v_cndmask_b32_e32 v82, v230, v96, vcc
	v_lshlrev_b32_e32 v100, 2, v82
	ds_bpermute_b32 v82, v100, v91
	s_waitcnt lgkmcnt(0)
; __device__ __forceinline__ void ew_phase(const Frame& F, const bf16_t* f, const float* gpost, float alpha, const float* hin, float* hout, const float* gpre, bf16_t* xn, ...
;     ...
;         const float rstd = alpha / sqrtf(wave_sum(s) * (1.f / DM) + RMS_EPS);
;         float s2 = 0.f; f32x4* ho = (f32x4*)(hout + (size_t)m * DM) + F.lane;
; #pragma unroll
;         for (int j = 0; j < 4; ++j) { hv[j] = hv[j] + fv[j] * rstd * gp[j]; if (out24) store24(h24 + (size_t)m * (DM * 3), F.lane + 64 * j, hv[j]); else ho[64 * j] = hv[j]; s2 += (hv[j].x * hv[j].x + hv[j].y * hv[j].y) + (hv[j].z * hv[j].z + hv[j].w * hv[j].w); }
;         if (gpre) {
;             const float r2 = 1.0f / sqrtf(wave_sum(s2) * (1.f / DM) + RMS_EPS);
	v_add_f32_e32 v82, v91, v82
	v_fmamk_f32 v82, v82, 0x3a800000, v225
	v_cmp_gt_f32_e32 vcc, s18, v82
	v_mul_f32_e32 v91, 0x4f800000, v82
	s_nop 0
	v_cndmask_b32_e32 v82, v82, v91, vcc
	v_sqrt_f32_e32 v91, v82
	s_nop 0
	v_add_u32_e32 v96, -1, v91
	v_fma_f32 v98, -v96, v91, v82
	v_cmp_ge_f32_e64 s[0:1], 0, v98
	v_add_u32_e32 v98, 1, v91
	s_nop 0
	v_cndmask_b32_e64 v96, v91, v96, s[0:1]
	v_fma_f32 v91, -v98, v91, v82
	v_cmp_lt_f32_e64 s[0:1], 0, v91
	s_nop 1
	v_cndmask_b32_e64 v91, v96, v98, s[0:1]
	v_mul_f32_e32 v96, 0x37800000, v91
	v_cndmask_b32_e32 v91, v91, v96, vcc
	v_cmp_class_f32_e32 vcc, v82, v226
	s_nop 1
	v_cndmask_b32_e32 v82, v91, v82, vcc
	v_div_scale_f32 v91, s[0:1], v82, v82, 0.5
	v_rcp_f32_e32 v96, v91
	s_mov_b32 s0, 0x7060503
	v_fma_f32 v98, -v91, v96, 1.0
	v_fmac_f32_e32 v96, v98, v96
	v_div_scale_f32 v98, vcc, 0.5, v82, 0.5
	v_mul_f32_e32 v99, v98, v96
	v_fma_f32 v101, -v91, v99, v98
	v_fmac_f32_e32 v99, v101, v96
	v_fma_f32 v91, -v91, v99, v98
	v_div_fmas_f32 v91, v91, v96, v99
	v_div_fixup_f32 v96, v91, v82, 0.5
	v_pk_mul_f32 v[54:55], v[96:97], v[54:55] op_sel_hi:[0,1]
	v_pk_mul_f32 v[56:57], v[96:97], v[56:57] op_sel_hi:[0,1]
	v_pk_fma_f32 v[52:53], v[4:5], v[56:57], v[52:53]
	v_pk_fma_f32 v[50:51], v[2:3], v[54:55], v[50:51]
	v_bfe_u32 v57, v52, 8, 1
	v_bfe_u32 v55, v51, 8, 1
	v_bfe_u32 v54, v50, 8, 1
	v_add3_u32 v55, v51, v55, s15
	v_add3_u32 v57, v52, v57, s15
	v_bfe_u32 v91, v53, 8, 1
	v_add3_u32 v54, v50, v54, s15
	v_lshrrev_b32_e32 v56, 8, v55
	v_lshrrev_b32_e32 v82, 8, v57
	v_add3_u32 v91, v53, v91, s15
	v_alignbit_b32 v54, v56, v54, 8
	v_alignbit_b32 v55, v82, v55, 16
	v_perm_b32 v56, v91, v57, s0
	global_store_dwordx3 v[48:49], v[54:56], off
	v_pk_mul_f32 v[48:49], v[52:53], v[52:53]
	v_mov_b32_e32 v82, v85
	v_pk_mul_f32 v[54:55], v[50:51], v[50:51]
	s_nop 0
	v_pk_mov_b32 v[56:57], v[54:55], v[48:49] op_sel:[1,0]
	v_mov_b32_e32 v55, v49
	v_pk_add_f32 v[48:49], v[54:55], v[56:57]
	s_nop 0
	v_pk_add_f32 v[98:99], v[48:49], v[48:49] op_sel_hi:[0,1]
	v_mov_b32_e32 v48, v66
	v_mov_b32_e32 v49, v64
	v_mov_b32_e32 v64, v67
	v_pk_mul_f32 v[54:55], v[96:97], v[48:49] op_sel_hi:[0,1]
	v_pk_mul_f32 v[48:49], v[96:97], v[64:65] op_sel_hi:[0,1]
	v_pk_fma_f32 v[48:49], v[8:9], v[48:49], v[62:63]
	v_pk_fma_f32 v[54:55], v[6:7], v[54:55], v[60:61]
	v_bfe_u32 v61, v48, 8, 1
	v_bfe_u32 v57, v55, 8, 1
	v_bfe_u32 v56, v54, 8, 1
	v_add3_u32 v57, v55, v57, s15
	v_add3_u32 v62, v48, v61, s15
	v_bfe_u32 v63, v49, 8, 1
	v_add3_u32 v56, v54, v56, s15
	v_lshrrev_b32_e32 v60, 8, v57
	v_lshrrev_b32_e32 v61, 8, v62
	v_add3_u32 v63, v49, v63, s15
	v_alignbit_b32 v60, v60, v56, 8
	v_alignbit_b32 v61, v61, v57, 16
	v_perm_b32 v62, v63, v62, s0
	global_store_dwordx3 v[58:59], v[60:62], off
	v_pk_mul_f32 v[56:57], v[48:49], v[48:49]
	v_pk_mul_f32 v[58:59], v[54:55], v[54:55]
	s_nop 0
	v_pk_mov_b32 v[60:61], v[58:59], v[56:57] op_sel:[1,0]
	v_mov_b32_e32 v59, v57
	v_pk_add_f32 v[56:57], v[58:59], v[60:61]
	v_pk_mul_f32 v[58:59], v[96:97], v[86:87] op_sel_hi:[0,1]
	v_pk_add_f32 v[66:67], v[56:57], v[56:57] op_sel_hi:[0,1]
	v_pk_mul_f32 v[56:57], v[96:97], v[88:89] op_sel_hi:[0,1]
	v_pk_fma_f32 v[56:57], v[20:21], v[56:57], v[78:79]
	v_pk_fma_f32 v[58:59], v[18:19], v[58:59], v[74:75]
	v_bfe_u32 v63, v56, 8, 1
	v_bfe_u32 v61, v59, 8, 1
	v_bfe_u32 v60, v58, 8, 1
	v_add3_u32 v61, v59, v61, s15
	v_add3_u32 v63, v56, v63, s15
	v_bfe_u32 v65, v57, 8, 1
	v_add3_u32 v60, v58, v60, s15
	v_lshrrev_b32_e32 v62, 8, v61
	v_lshrrev_b32_e32 v64, 8, v63
	v_add3_u32 v65, v57, v65, s15
	v_alignbit_b32 v60, v62, v60, 8
	v_alignbit_b32 v61, v64, v61, 16
	v_perm_b32 v62, v65, v63, s0
	global_store_dwordx3 v[70:71], v[60:62], off
	s_nop 1
	v_mul_f32_e32 v60, v58, v58
	v_pk_fma_f32 v[70:71], v[58:59], v[58:59], v[60:61] op_sel_hi:[1,1,0]
	v_mul_f32_e32 v60, v56, v56
	v_pk_fma_f32 v[74:75], v[56:57], v[56:57], v[60:61] op_sel_hi:[1,1,0]
	v_pk_mul_f32 v[62:63], v[82:83], v[96:97] op_sel_hi:[1,0]
	v_pk_mul_f32 v[60:61], v[80:81], v[96:97] op_sel_hi:[1,0]
	v_pk_fma_f32 v[62:63], v[22:23], v[62:63], v[72:73]
	v_pk_fma_f32 v[60:61], v[24:25], v[60:61], v[76:77]
	v_bfe_u32 v65, v63, 8, 1
	v_bfe_u32 v70, v60, 8, 1
	v_bfe_u32 v64, v62, 8, 1
	v_add3_u32 v65, v63, v65, s15
	v_add3_u32 v70, v60, v70, s15
	v_bfe_u32 v73, v61, 8, 1
	v_add3_u32 v64, v62, v64, s15
	v_lshrrev_b32_e32 v66, 8, v65
	v_lshrrev_b32_e32 v72, 8, v70
	v_add3_u32 v73, v61, v73, s15
	v_alignbit_b32 v64, v66, v64, 8
	v_alignbit_b32 v65, v72, v65, 16
	v_perm_b32 v66, v73, v70, s0
	global_store_dwordx3 v[68:69], v[64:66], off
	v_mul_f32_e32 v70, v62, v62
	v_mul_f32_e32 v74, v63, v63
	v_mul_f32_e32 v98, v61, v61
	v_mul_f32_e32 v66, v60, v60
	v_pk_add_f32 v[64:65], v[70:71], v[74:75]
	v_pk_add_f32 v[66:67], v[98:99], v[66:67]
	s_nop 0
	v_pk_add_f32 v[64:65], v[64:65], v[66:67]
	s_nop 0
	v_add_f32_e32 v64, v64, v65
	s_nop 1
	v_add_f32_dpp v0, v64, v64 quad_perm:[1,0,3,2] row_mask:0xf bank_mask:0xf
	s_nop 1
	v_add_f32_dpp v0, v0, v0 quad_perm:[2,3,0,1] row_mask:0xf bank_mask:0xf
	s_nop 1
	v_add_f32_dpp v0, v0, v0 row_half_mirror row_mask:0xf bank_mask:0xf
	s_nop 1
	v_add_f32_dpp v0, v0, v0 row_mirror row_mask:0xf bank_mask:0xf
	ds_bpermute_b32 v35, v97, v0
	s_waitcnt lgkmcnt(0)
; __device__ __forceinline__ unsigned cvt_pk_bf16(float lo, float hi) { f32x2 v = {lo, hi}; bf16x2_t b = __builtin_convertvector(v, bf16x2_t); return __builtin_bit_cast(unsigned, b); }
; __device__ __forceinline__ void ew_phase(const Frame& F, const bf16_t* f, const float* gpost, float alpha, const float* hin, float* hout, const float* gpre, bf16_t* xn, ...
;     ...
;             const float r2 = 1.0f / sqrtf(wave_sum(s2) * (1.f / DM) + RMS_EPS);
;             u32x2* o8 = (u32x2*)(xn + (size_t)m * DM) + F.lane;
; #pragma unroll
;             for (int j = 0; j < 4; ++j) { hv[j] = hv[j] * r2 * gq[j]; u32x2 w; w.x = cvt_pk_bf16(hv[j].x, hv[j].y); w.y = cvt_pk_bf16(hv[j].z, hv[j].w); o8[64 * j] = w; }
	v_add_f32_e32 v0, v0, v35
	ds_bpermute_b32 v35, v100, v0
	s_waitcnt lgkmcnt(0)
	v_add_f32_e32 v0, v0, v35
	v_fmamk_f32 v0, v0, 0x3a800000, v225
	v_cmp_gt_f32_e32 vcc, s18, v0
	v_mul_f32_e32 v35, 0x4f800000, v0
	s_nop 0
	v_cndmask_b32_e32 v0, v0, v35, vcc
	v_sqrt_f32_e32 v35, v0
	s_nop 0
	v_add_u32_e32 v64, -1, v35
	v_fma_f32 v65, -v64, v35, v0
	v_cmp_ge_f32_e64 s[0:1], 0, v65
	v_add_u32_e32 v65, 1, v35
	s_nop 0
	v_cndmask_b32_e64 v64, v35, v64, s[0:1]
	v_fma_f32 v35, -v65, v35, v0
	v_cmp_lt_f32_e64 s[0:1], 0, v35
	s_nop 1
	v_cndmask_b32_e64 v35, v64, v65, s[0:1]
	v_mul_f32_e32 v64, 0x37800000, v35
	v_cndmask_b32_e32 v35, v35, v64, vcc
	v_cmp_class_f32_e32 vcc, v0, v226
	s_nop 1
	v_cndmask_b32_e32 v0, v35, v0, vcc
	v_div_scale_f32 v35, s[0:1], v0, v0, 1.0
	v_rcp_f32_e32 v64, v35
	s_cselect_b64 s[0:1], -1, 0
	v_fma_f32 v65, -v35, v64, 1.0
	v_fmac_f32_e32 v64, v65, v64
	v_div_scale_f32 v65, vcc, 1.0, v0, 1.0
	v_mul_f32_e32 v66, v65, v64
	v_fma_f32 v67, -v35, v66, v65
	v_fmac_f32_e32 v66, v67, v64
	v_fma_f32 v35, -v35, v66, v65
	v_div_fmas_f32 v35, v35, v64, v66
	v_div_fixup_f32 v0, v35, v0, 1.0
	v_pk_mul_f32 v[50:51], v[50:51], v[0:1] op_sel_hi:[1,0]
	v_pk_mul_f32 v[52:53], v[52:53], v[0:1] op_sel_hi:[1,0]
	v_pk_mul_f32 v[50:51], v[10:11], v[50:51]
	v_pk_mul_f32 v[52:53], v[12:13], v[52:53]
	v_lshl_add_u64 v[64:65], v[46:47], 0, s[6:7]
	v_cvt_pk_bf16_f32 v50, v50, v51
	v_cvt_pk_bf16_f32 v51, v52, v53
	global_store_dwordx2 v[64:65], v[50:51], off
	v_pk_mul_f32 v[50:51], v[54:55], v[0:1] op_sel_hi:[1,0]
	v_pk_mul_f32 v[48:49], v[48:49], v[0:1] op_sel_hi:[1,0]
	v_pk_mul_f32 v[50:51], v[14:15], v[50:51]
	v_pk_mul_f32 v[48:49], v[16:17], v[48:49]
	v_cvt_pk_bf16_f32 v50, v50, v51
	v_cvt_pk_bf16_f32 v51, v48, v49
	global_store_dwordx2 v[64:65], v[50:51], off offset:512
	v_pk_mul_f32 v[48:49], v[58:59], v[0:1] op_sel_hi:[1,0]
	v_pk_mul_f32 v[50:51], v[56:57], v[0:1] op_sel_hi:[1,0]
	v_pk_mul_f32 v[48:49], v[26:27], v[48:49]
	v_pk_mul_f32 v[50:51], v[28:29], v[50:51]
	v_cvt_pk_bf16_f32 v48, v48, v49
	v_cvt_pk_bf16_f32 v49, v50, v51
	global_store_dwordx2 v[64:65], v[48:49], off offset:1024
	v_pk_mul_f32 v[48:49], v[62:63], v[0:1] op_sel_hi:[1,0]
	v_pk_mul_f32 v[50:51], v[60:61], v[0:1] op_sel_hi:[1,0]
	v_pk_mul_f32 v[48:49], v[30:31], v[48:49]
	v_pk_mul_f32 v[50:51], v[32:33], v[50:51]
	v_cvt_pk_bf16_f32 v48, v48, v49
	v_cvt_pk_bf16_f32 v49, v50, v51
	global_store_dwordx2 v[64:65], v[48:49], off offset:1536
	s_branch .LBB0_904
